# v6 + hgrn workgroups skip gdnpre (others take their tasks) and run first 8 chain chunks during it, suspend/resume across the barrier
# speedup vs baseline: 1.0446x; 1.0446x over previous
.LBB0_15:
	s_mov_b64 s[80:81], s[66:67]
	v_mov_b32_e32 v186, v236
	s_mov_b32 s64, s62
	s_load_dword s75, s[66:67], 0x108
	s_waitcnt lgkmcnt(0)
	s_load_dwordx2 s[78:79], s[80:81], 0xf8
	s_memrealtime s[4:5]
	v_writelane_b32 v255, s2, 22
	s_movk_i32 s101, 0x7fff
	s_cmp_eq_u32 s2, 4
	s_cbranch_scc1 .Lhs_p3
	s_cmp_eq_u32 s2, 15
	s_cbranch_scc1 .Lhs_p3
	s_branch .Lhs_done
.Lhs_p3:
	s_movk_i32 s101, 8
	s_cmp_lt_u32 s62, 64
	s_cbranch_scc1 .Lhs_done
	s_sub_u32 s64, s62, 64
	s_movk_i32 s75, 0xc0

.LBB0_336:
	s_andn2_b64 vcc, exec, s[4:5]
	s_cbranch_vccnz .LBB0_911
	v_readlane_b32 s0, v255, 25
	s_cmp_lt_u32 s62, 64
	s_cbranch_scc0 .Lhs_nored
	s_cmp_eq_u32 s0, 3
	s_cbranch_scc0 .Lhs_nored
	s_mov_b64 s[4:5], -1
	s_branch .Lhs_mix
